# attention: map-1 Q fragments held in registers too (ALiBi multiples moved to SGPRs, phase invariants parked in static LDS)
# speedup vs baseline: 1.0288x; 1.0025x over previous
.LBB0_222:
	v_add_f32_e32 v0, v147, v149
	v_add_f32_e32 v1, v145, v148
	v_mul_f32_e32 v0, 0x3fb8aa3b, v0
	v_mul_f32_e32 v1, 0x3fb8aa3b, v1
	v_exp_f32_e32 v0, v0
	v_exp_f32_e32 v1, v1
	v_and_b32_e32 v4, 16, v183
	v_mov_b32_e32 v6, 0x19800
	v_mov_b32_e32 v7, 0x11000
	v_sub_f32_e32 v0, v0, v1
	v_lshrrev_b32_e32 v1, 4, v183
	v_cmp_eq_u32_e32 vcc, 0, v4
	v_add_f32_e32 v172, 0x3e4ccccd, v0
	v_mul_u32_u24_e32 v0, 0x6000, v1
	v_cndmask_b32_e32 v4, v6, v7, vcc
	v_and_b32_e32 v6, 0xf0, v134
	v_lshl_or_b32 v0, v169, 3, v0
	v_lshrrev_b32_e32 v5, 5, v183
	v_add3_u32 v7, 0, v4, v6
	v_add_u32_e32 v4, 0x200, v183
	v_add_u32_e32 v173, 0x2800, v0
	v_mul_u32_u24_e32 v0, 0x6000, v5
	v_and_b32_e32 v171, 31, v183
	v_lshrrev_b32_e32 v8, 5, v4
	v_lshl_or_b32 v2, v171, 3, v0
	v_mul_u32_u24_e32 v4, 0x6000, v8
	v_mul_u32_u24_e32 v13, 0x110, v8
	v_add_u32_e32 v8, 0xa00, v183
	v_bfe_u32 v3, v183, 4, 2
	v_add_u32_e32 v174, 0x3000, v2
	v_lshlrev_b32_e32 v2, 4, v169
	s_movk_i32 s3, 0x110
	v_lshrrev_b32_e32 v12, 5, v8
	v_mad_u32_u24 v175, v1, s3, v2
	v_lshlrev_b32_e32 v1, 4, v171
	v_mul_u32_u24_e32 v8, 0x6000, v12
	v_mul_u32_u24_e32 v15, 0x110, v12
	s_movk_i32 s0, 0x220
	v_lshlrev_b32_e32 v12, 2, v3
	v_add_u32_e32 v6, 0x600, v183
	v_add_u32_e32 v10, 0xe00, v183
	v_mad_u32_u24 v176, v5, s0, v1
	v_or_b32_e32 v1, v12, v73
	v_lshrrev_b32_e32 v9, 5, v6
	v_lshrrev_b32_e32 v14, 5, v10
	v_mul_u32_u24_e32 v1, 0x220, v1
	v_and_b32_e32 v2, 0xf8, v170
	v_mov_b32_e32 v145, 0
	v_mul_u32_u24_e32 v6, 0x6000, v9
	v_mul_u32_u24_e32 v11, 0x110, v5
	v_mul_u32_u24_e32 v9, 0x110, v9
	v_mul_u32_u24_e32 v10, 0x6000, v14
	v_mul_u32_u24_e32 v14, 0x110, v14
	v_lshlrev_b32_e32 v144, 4, v3
	v_readlane_b32 s0, v239, 30
	v_add3_u32 v179, 0, v1, v132
	v_sub_u32_e32 v1, v169, v12
	s_add_i32 s24, 0, 0x22000
	v_readlane_b32 s80, v239, 26
	s_mov_b32 s17, 0
	v_add_u32_e32 v177, s0, v144
	v_lshl_add_u64 v[146:147], s[58:59], 0, v[144:145]
	v_add3_u32 v178, 0, v144, v133
	v_add_u32_e32 v180, 0x780, v1
	v_mov_b32_e32 v181, s24
	s_movk_i32 s25, 0x1ff
	s_mov_b32 s26, 0xc000
	v_lshlrev_b32_e32 v148, 1, v2
	s_mov_b64 s[18:19], 0x4000
	v_lshlrev_b32_e32 v150, 1, v0
	v_lshlrev_b32_e32 v152, 1, v4
	s_mov_b32 s27, 0x180000
	v_lshlrev_b32_e32 v154, 1, v6
	v_add_u32_e32 v184, v7, v11
	v_add_u32_e32 v185, v7, v13
	v_add_u32_e32 v186, v7, v9
	s_mov_b32 s28, 0x300000
	v_lshlrev_b32_e32 v156, 1, v8
	s_mov_b32 s29, 0x480000
	v_lshlrev_b32_e32 v158, 1, v10
	v_add_u32_e32 v187, v7, v15
	v_add_u32_e32 v188, v7, v14
	s_mov_b32 s30, 0xc0000
	v_add_u32_e32 v189, 0, v175
	v_add_u32_e32 v190, 0, v176
	s_mov_b32 s31, 0x240000
	s_mov_b32 s33, 0xf149f2ca
	v_mov_b32_e32 v191, 0x3727c5ac
	s_mov_b32 s34, 0x800000
	v_lshlrev_b32_e32 v160, 1, v12
	s_mov_b64 s[20:21], 0x7000
	s_movk_i32 s35, 0x7000
	v_mov_b32_e32 v192, 0xf149f2ca
	v_readlane_b32 s81, v239, 27
	v_readlane_b32 s82, v239, 28
	v_readlane_b32 s83, v239, 29
	v_lshlrev_b32_e32 v0, 2, v183
	v_add_u32_e32 v0, 0x22100, v0
	ds_write_b32 v0, v148
	ds_write_b32 v0, v150 offset:2048
	ds_write_b32 v0, v152 offset:4096
	ds_write_b32 v0, v154 offset:6144
	ds_write_b32 v0, v156 offset:8192
	ds_write_b32 v0, v158 offset:10240
	ds_write_b32 v0, v184 offset:12288
	ds_write_b32 v0, v185 offset:14336
	ds_write_b32 v0, v186 offset:16384
	ds_write_b32 v0, v187 offset:18432
	s_branch .LBB0_225
.LBB0_223:
	v_lshlrev_b32_e32 v238, 2, v183
	v_add_u32_e32 v238, 0x22100, v238
	ds_read_b32 v148, v238
	ds_read_b32 v150, v238 offset:2048
	ds_read_b32 v152, v238 offset:4096
	ds_read_b32 v154, v238 offset:6144
	ds_read_b32 v156, v238 offset:8192
	ds_read_b32 v158, v238 offset:10240
	ds_read_b32 v184, v238 offset:12288
	ds_read_b32 v185, v238 offset:14336
	ds_read_b32 v186, v238 offset:16384
	ds_read_b32 v187, v238 offset:18432
	s_waitcnt lgkmcnt(0)
	s_waitcnt vmcnt(2)
	v_mov_b32_e32 v116, v165
	s_nop 1
	v_permlane16_swap_b32_e32 v165, v116
	v_add_f32_e32 v116, v165, v116
	v_mov_b32_e32 v117, v116
	s_nop 1
	v_permlane32_swap_b32_e32 v116, v117
	v_add_f32_e32 v116, v116, v117
	v_div_scale_f32 v117, s[0:1], v116, v116, 1.0
	v_rcp_f32_e32 v118, v117
	s_waitcnt vmcnt(1)
	v_or_b32_e32 v125, s37, v169
	v_add_u32_e32 v144, s16, v125
	s_lshl_b32 s16, s36, 1
	v_fma_f32 v119, -v117, v118, 1.0
	v_fmac_f32_e32 v118, v119, v118
	v_div_scale_f32 v119, vcc, 1.0, v116, 1.0
	v_mul_f32_e32 v124, v119, v118
	v_fma_f32 v126, -v117, v124, v119
	v_fmac_f32_e32 v124, v126, v118
	v_fma_f32 v117, -v117, v124, v119
	v_mov_b32_e32 v119, v164
	s_nop 1
	v_permlane16_swap_b32_e32 v164, v119
	v_add_f32_e32 v119, v164, v119
	v_mov_b32_e32 v126, v119
	s_nop 1
	v_permlane32_swap_b32_e32 v119, v126
	v_add_f32_e32 v119, v119, v126
	v_div_scale_f32 v126, s[0:1], v119, v119, 1.0
	v_rcp_f32_e32 v127, v126
	v_div_fmas_f32 v117, v117, v118, v124
	v_div_fixup_f32 v124, v117, v116, 1.0
	v_mov_b32_e32 v161, v145
	v_fma_f32 v116, -v126, v127, 1.0
	v_fmac_f32_e32 v127, v116, v127
	v_div_scale_f32 v116, vcc, 1.0, v119, 1.0
	v_mul_f32_e32 v117, v116, v127
	v_fma_f32 v118, -v126, v117, v116
	v_fmac_f32_e32 v117, v118, v127
	v_fma_f32 v116, -v126, v117, v116
	v_div_fmas_f32 v116, v116, v127, v117
	v_div_fixup_f32 v116, v116, v119, 1.0
	v_mul_f32_e32 v126, v172, v116
	v_pk_mul_f32 v[118:119], v[128:129], v[126:127] op_sel_hi:[1,0]
	v_pk_mul_f32 v[116:117], v[130:131], v[126:127] op_sel_hi:[1,0]
	v_pk_fma_f32 v[118:119], v[136:137], v[124:125], v[118:119] op_sel_hi:[1,0,1] neg_lo:[0,0,1] neg_hi:[0,0,1]
	v_pk_fma_f32 v[116:117], v[138:139], v[124:125], v[116:117] op_sel_hi:[1,0,1] neg_lo:[0,0,1] neg_hi:[0,0,1]
	v_mul_f32_e32 v127, v119, v119
	v_mul_f32_e32 v128, v117, v117
	v_fmac_f32_e32 v127, v118, v118
	v_fmac_f32_e32 v128, v116, v116
	v_add_f32_e32 v127, v127, v128
	v_pk_mul_f32 v[128:129], v[112:113], v[126:127] op_sel_hi:[1,0]
	v_pk_mul_f32 v[112:113], v[114:115], v[126:127] op_sel_hi:[1,0]
	v_pk_fma_f32 v[114:115], v[120:121], v[124:125], v[128:129] op_sel_hi:[1,0,1] neg_lo:[0,0,1] neg_hi:[0,0,1]
	v_pk_fma_f32 v[112:113], v[122:123], v[124:125], v[112:113] op_sel_hi:[1,0,1] neg_lo:[0,0,1] neg_hi:[0,0,1]
	v_mul_f32_e32 v120, v115, v115
	v_mul_f32_e32 v121, v113, v113
	v_fmac_f32_e32 v120, v114, v114
	v_fmac_f32_e32 v121, v112, v112
	v_add_f32_e32 v120, v120, v121
	v_add_f32_e32 v122, v127, v120
	v_pk_mul_f32 v[120:121], v[104:105], v[126:127] op_sel_hi:[1,0]
	v_pk_mul_f32 v[104:105], v[106:107], v[126:127] op_sel_hi:[1,0]
	v_pk_fma_f32 v[106:107], v[108:109], v[124:125], v[120:121] op_sel_hi:[1,0,1] neg_lo:[0,0,1] neg_hi:[0,0,1]
	v_pk_fma_f32 v[104:105], v[110:111], v[124:125], v[104:105] op_sel_hi:[1,0,1] neg_lo:[0,0,1] neg_hi:[0,0,1]
	v_mul_f32_e32 v108, v107, v107
	v_mul_f32_e32 v109, v105, v105
	v_fmac_f32_e32 v108, v106, v106
	v_fmac_f32_e32 v109, v104, v104
	v_add_f32_e32 v108, v108, v109
	v_add_f32_e32 v110, v108, v122
	v_pk_mul_f32 v[108:109], v[96:97], v[126:127] op_sel_hi:[1,0]
	v_pk_mul_f32 v[96:97], v[98:99], v[126:127] op_sel_hi:[1,0]
	v_pk_fma_f32 v[98:99], v[100:101], v[124:125], v[108:109] op_sel_hi:[1,0,1] neg_lo:[0,0,1] neg_hi:[0,0,1]
	v_pk_fma_f32 v[96:97], v[102:103], v[124:125], v[96:97] op_sel_hi:[1,0,1] neg_lo:[0,0,1] neg_hi:[0,0,1]
	v_mul_f32_e32 v100, v99, v99
	v_mul_f32_e32 v101, v97, v97
	v_fmac_f32_e32 v100, v98, v98
	v_fmac_f32_e32 v101, v96, v96
	v_add_f32_e32 v100, v100, v101
	v_add_f32_e32 v102, v100, v110
	v_pk_mul_f32 v[100:101], v[88:89], v[126:127] op_sel_hi:[1,0]
	v_pk_mul_f32 v[88:89], v[90:91], v[126:127] op_sel_hi:[1,0]
	v_pk_fma_f32 v[90:91], v[92:93], v[124:125], v[100:101] op_sel_hi:[1,0,1] neg_lo:[0,0,1] neg_hi:[0,0,1]
	v_pk_fma_f32 v[88:89], v[94:95], v[124:125], v[88:89] op_sel_hi:[1,0,1] neg_lo:[0,0,1] neg_hi:[0,0,1]
	v_mul_f32_e32 v92, v91, v91
	v_mul_f32_e32 v93, v89, v89
	v_fmac_f32_e32 v92, v90, v90
	v_fmac_f32_e32 v93, v88, v88
	v_add_f32_e32 v92, v92, v93
	v_add_f32_e32 v94, v92, v102
	v_pk_mul_f32 v[92:93], v[80:81], v[126:127] op_sel_hi:[1,0]
	v_pk_mul_f32 v[80:81], v[82:83], v[126:127] op_sel_hi:[1,0]
	v_pk_fma_f32 v[82:83], v[84:85], v[124:125], v[92:93] op_sel_hi:[1,0,1] neg_lo:[0,0,1] neg_hi:[0,0,1]
	v_pk_fma_f32 v[80:81], v[86:87], v[124:125], v[80:81] op_sel_hi:[1,0,1] neg_lo:[0,0,1] neg_hi:[0,0,1]
	v_mul_f32_e32 v84, v83, v83
	v_mul_f32_e32 v85, v81, v81
	v_fmac_f32_e32 v84, v82, v82
	v_fmac_f32_e32 v85, v80, v80
	v_add_f32_e32 v84, v84, v85
	v_add_f32_e32 v86, v84, v94
	v_pk_mul_f32 v[84:85], v[72:73], v[126:127] op_sel_hi:[1,0]
	v_pk_mul_f32 v[72:73], v[74:75], v[126:127] op_sel_hi:[1,0]
	v_pk_fma_f32 v[74:75], v[76:77], v[124:125], v[84:85] op_sel_hi:[1,0,1] neg_lo:[0,0,1] neg_hi:[0,0,1]
	v_pk_fma_f32 v[72:73], v[78:79], v[124:125], v[72:73] op_sel_hi:[1,0,1] neg_lo:[0,0,1] neg_hi:[0,0,1]
	v_mul_f32_e32 v76, v75, v75
	v_mul_f32_e32 v77, v73, v73
	v_fmac_f32_e32 v76, v74, v74
	v_fmac_f32_e32 v77, v72, v72
	v_add_f32_e32 v76, v76, v77
	v_add_f32_e32 v78, v76, v86
	v_pk_mul_f32 v[76:77], v[64:65], v[126:127] op_sel_hi:[1,0]
	v_pk_mul_f32 v[64:65], v[66:67], v[126:127] op_sel_hi:[1,0]
	v_pk_fma_f32 v[66:67], v[68:69], v[124:125], v[76:77] op_sel_hi:[1,0,1] neg_lo:[0,0,1] neg_hi:[0,0,1]
	v_pk_fma_f32 v[64:65], v[70:71], v[124:125], v[64:65] op_sel_hi:[1,0,1] neg_lo:[0,0,1] neg_hi:[0,0,1]
	v_mul_f32_e32 v68, v67, v67
	v_mul_f32_e32 v69, v65, v65
	v_fmac_f32_e32 v68, v66, v66
	v_fmac_f32_e32 v69, v64, v64
	v_add_f32_e32 v68, v68, v69
	v_add_f32_e32 v70, v68, v78
	v_pk_mul_f32 v[68:69], v[56:57], v[126:127] op_sel_hi:[1,0]
	v_pk_mul_f32 v[56:57], v[58:59], v[126:127] op_sel_hi:[1,0]
	v_pk_fma_f32 v[58:59], v[60:61], v[124:125], v[68:69] op_sel_hi:[1,0,1] neg_lo:[0,0,1] neg_hi:[0,0,1]
	v_pk_fma_f32 v[56:57], v[62:63], v[124:125], v[56:57] op_sel_hi:[1,0,1] neg_lo:[0,0,1] neg_hi:[0,0,1]
	v_pk_mul_f32 v[40:41], v[40:41], v[126:127] op_sel_hi:[1,0]
	v_pk_mul_f32 v[42:43], v[42:43], v[126:127] op_sel_hi:[1,0]
	v_mul_f32_e32 v60, v59, v59
	v_mul_f32_e32 v61, v57, v57
	v_pk_fma_f32 v[50:51], v[50:51], v[124:125], v[42:43] op_sel_hi:[1,0,1] neg_lo:[0,0,1] neg_hi:[0,0,1]
	v_pk_fma_f32 v[48:49], v[48:49], v[124:125], v[40:41] op_sel_hi:[1,0,1] neg_lo:[0,0,1] neg_hi:[0,0,1]
	v_fmac_f32_e32 v60, v58, v58
	v_fmac_f32_e32 v61, v56, v56
	v_mul_f32_e32 v40, v49, v49
	v_mul_f32_e32 v41, v51, v51
	v_pk_mul_f32 v[42:43], v[52:53], v[126:127] op_sel_hi:[1,0]
	v_add_f32_e32 v60, v60, v61
	v_fmac_f32_e32 v40, v48, v48
	v_fmac_f32_e32 v41, v50, v50
	v_pk_fma_f32 v[42:43], v[44:45], v[124:125], v[42:43] op_sel_hi:[1,0,1] neg_lo:[0,0,1] neg_hi:[0,0,1]
	v_mov_b64_e32 v[44:45], s[74:75]
	v_add_f32_e32 v60, v60, v70
	v_add_f32_e32 v40, v40, v41
	v_mad_u64_u32 v[44:45], s[0:1], v144, s26, v[44:45]
	v_add_f32_e32 v60, v40, v60
	v_pk_mul_f32 v[40:41], v[54:55], v[126:127] op_sel_hi:[1,0]
	v_lshl_add_u64 v[44:45], v[44:45], 0, s[16:17]
	v_pk_fma_f32 v[40:41], v[46:47], v[124:125], v[40:41] op_sel_hi:[1,0,1] neg_lo:[0,0,1] neg_hi:[0,0,1]
	v_lshl_add_u64 v[46:47], v[44:45], 0, v[160:161]
	v_add_co_u32_e32 v44, vcc, s35, v46
	v_mul_f32_e32 v52, v43, v43
	s_nop 0
	v_addc_co_u32_e32 v45, vcc, 0, v47, vcc
	global_load_dwordx2 v[44:45], v[44:45], off
	v_mul_f32_e32 v53, v41, v41
	v_fmac_f32_e32 v52, v42, v42
	v_fmac_f32_e32 v53, v40, v40
	v_add_f32_e32 v52, v52, v53
	v_add_f32_e32 v54, v52, v60
	v_pk_mul_f32 v[52:53], v[36:37], v[126:127] op_sel_hi:[1,0]
	v_pk_mul_f32 v[36:37], v[38:39], v[126:127] op_sel_hi:[1,0]
	v_pk_fma_f32 v[38:39], v[28:29], v[124:125], v[52:53] op_sel_hi:[1,0,1] neg_lo:[0,0,1] neg_hi:[0,0,1]
	v_pk_fma_f32 v[36:37], v[30:31], v[124:125], v[36:37] op_sel_hi:[1,0,1] neg_lo:[0,0,1] neg_hi:[0,0,1]
	global_load_dwordx4 v[28:31], v[146:147], off
	v_pk_mul_f32 v[32:33], v[32:33], v[126:127] op_sel_hi:[1,0]
	v_pk_mul_f32 v[34:35], v[34:35], v[126:127] op_sel_hi:[1,0]
	v_mul_f32_e32 v52, v39, v39
	v_mul_f32_e32 v53, v37, v37
	v_pk_fma_f32 v[18:19], v[18:19], v[124:125], v[34:35] op_sel_hi:[1,0,1] neg_lo:[0,0,1] neg_hi:[0,0,1]
	v_pk_fma_f32 v[32:33], v[16:17], v[124:125], v[32:33] op_sel_hi:[1,0,1] neg_lo:[0,0,1] neg_hi:[0,0,1]
	v_fmac_f32_e32 v52, v38, v38
	v_fmac_f32_e32 v53, v36, v36
	v_mul_f32_e32 v16, v33, v33
	v_mul_f32_e32 v17, v19, v19
	v_add_f32_e32 v52, v52, v53
	v_fmac_f32_e32 v16, v32, v32
	v_fmac_f32_e32 v17, v18, v18
	v_add_f32_e32 v52, v52, v54
	v_add_f32_e32 v16, v16, v17
	v_add_f32_e32 v34, v16, v52
	v_pk_mul_f32 v[16:17], v[24:25], v[126:127] op_sel_hi:[1,0]
	v_pk_mul_f32 v[24:25], v[26:27], v[126:127] op_sel_hi:[1,0]
	v_pk_fma_f32 v[16:17], v[8:9], v[124:125], v[16:17] op_sel_hi:[1,0,1] neg_lo:[0,0,1] neg_hi:[0,0,1]
	v_pk_fma_f32 v[10:11], v[10:11], v[124:125], v[24:25] op_sel_hi:[1,0,1] neg_lo:[0,0,1] neg_hi:[0,0,1]
	v_mul_f32_e32 v8, v17, v17
	v_mul_f32_e32 v9, v11, v11
	v_fmac_f32_e32 v8, v16, v16
	v_fmac_f32_e32 v9, v10, v10
	v_add_f32_e32 v8, v8, v9
	v_add_f32_e32 v24, v8, v34
	v_pk_mul_f32 v[8:9], v[20:21], v[126:127] op_sel_hi:[1,0]
	v_pk_mul_f32 v[20:21], v[22:23], v[126:127] op_sel_hi:[1,0]
	v_pk_fma_f32 v[8:9], v[4:5], v[124:125], v[8:9] op_sel_hi:[1,0,1] neg_lo:[0,0,1] neg_hi:[0,0,1]
	v_pk_fma_f32 v[6:7], v[6:7], v[124:125], v[20:21] op_sel_hi:[1,0,1] neg_lo:[0,0,1] neg_hi:[0,0,1]
	v_mul_f32_e32 v4, v9, v9
	v_mul_f32_e32 v5, v7, v7
	v_fmac_f32_e32 v4, v8, v8
	v_fmac_f32_e32 v5, v6, v6
	v_add_f32_e32 v4, v4, v5
	v_add_f32_e32 v20, v4, v24
	v_pk_mul_f32 v[4:5], v[12:13], v[126:127] op_sel_hi:[1,0]
	v_pk_mul_f32 v[12:13], v[14:15], v[126:127] op_sel_hi:[1,0]
	v_pk_fma_f32 v[0:1], v[0:1], v[124:125], v[4:5] op_sel_hi:[1,0,1] neg_lo:[0,0,1] neg_hi:[0,0,1]
	v_pk_fma_f32 v[2:3], v[2:3], v[124:125], v[12:13] op_sel_hi:[1,0,1] neg_lo:[0,0,1] neg_hi:[0,0,1]
	v_mul_f32_e32 v4, v1, v1
	v_mul_f32_e32 v5, v3, v3
	v_fmac_f32_e32 v4, v0, v0
	v_fmac_f32_e32 v5, v2, v2
	v_add_f32_e32 v4, v4, v5
	v_add_f32_e32 v4, v4, v20
	v_mov_b32_e32 v5, v4
	s_nop 1
	v_permlane16_swap_b32_e32 v4, v5
	v_add_f32_e32 v4, v4, v5
	v_mov_b32_e32 v5, v4
	s_nop 1
	v_permlane32_swap_b32_e32 v4, v5
	v_add_f32_e32 v4, v4, v5
	v_fmamk_f32 v4, v4, 0x3b800000, v191
	v_mul_f32_e32 v5, 0x4b800000, v4
	v_cmp_gt_f32_e32 vcc, s34, v4
	v_lshlrev_b64 v[12:13], 12, v[144:145]
	v_lshl_add_u64 v[14:15], s[98:99], 0, v[12:13]
	v_cndmask_b32_e32 v4, v4, v5, vcc
	v_rsq_f32_e32 v4, v4
	v_lshl_add_u64 v[12:13], v[46:47], 0, s[20:21]
	global_load_dwordx2 v[20:21], v[12:13], off offset:480
	v_lshl_add_u64 v[14:15], v[14:15], 0, s[16:17]
	v_mul_f32_e32 v5, 0x45800000, v4
	v_cndmask_b32_e32 v4, v4, v5, vcc
	v_mul_f32_e32 v4, 0x3f4ccccd, v4
	v_lshl_add_u64 v[14:15], v[14:15], 0, v[160:161]
	s_mov_b64 s[0:1], 0
	global_load_dwordx4 v[120:123], v[146:147], off offset:64
	global_load_dwordx2 v[22:23], v[12:13], off offset:32
	global_load_dwordx4 v[124:127], v[146:147], off offset:128
	global_load_dwordx2 v[24:25], v[12:13], off offset:64
	global_load_dwordx4 v[128:131], v[146:147], off offset:192
	global_load_dwordx2 v[26:27], v[12:13], off offset:96
	global_load_dwordx4 v[132:135], v[146:147], off offset:256
	global_load_dwordx2 v[34:35], v[12:13], off offset:128
	global_load_dwordx4 v[136:139], v[146:147], off offset:320
	global_load_dwordx2 v[46:47], v[12:13], off offset:160
	global_load_dwordx4 v[140:143], v[146:147], off offset:384
	global_load_dwordx2 v[52:53], v[12:13], off offset:192
	global_load_dwordx4 v[196:199], v[146:147], off offset:448
	global_load_dwordx2 v[54:55], v[12:13], off offset:224
	global_load_dwordx4 v[200:203], v[146:147], off offset:512
	global_load_dwordx2 v[60:61], v[12:13], off offset:256
	global_load_dwordx4 v[204:207], v[146:147], off offset:576
	global_load_dwordx2 v[62:63], v[12:13], off offset:288
	global_load_dwordx4 v[208:211], v[146:147], off offset:640
	global_load_dwordx2 v[68:69], v[12:13], off offset:320
	global_load_dwordx4 v[212:215], v[146:147], off offset:704
	global_load_dwordx2 v[70:71], v[12:13], off offset:352
	global_load_dwordx4 v[216:219], v[146:147], off offset:768
	global_load_dwordx2 v[76:77], v[12:13], off offset:384
	global_load_dwordx4 v[220:223], v[146:147], off offset:832
	global_load_dwordx2 v[78:79], v[12:13], off offset:416
	global_load_dwordx4 v[224:227], v[146:147], off offset:896
	global_load_dwordx2 v[84:85], v[12:13], off offset:448
	global_load_dwordx4 v[228:231], v[146:147], off offset:960
	s_waitcnt vmcnt(30)
	v_lshlrev_b32_e32 v92, 16, v44
	v_and_b32_e32 v93, 0xffff0000, v44
	v_lshlrev_b32_e32 v94, 16, v45
	v_and_b32_e32 v95, 0xffff0000, v45
	v_mul_f32_e32 v100, 0xbfb8aa3b, v92
	v_mul_f32_e32 v101, 0xbfb8aa3b, v93
	v_mul_f32_e32 v102, 0xbfb8aa3b, v94
	v_mul_f32_e32 v103, 0xbfb8aa3b, v95
	v_exp_f32_e32 v100, v100
	v_exp_f32_e32 v101, v101
	v_exp_f32_e32 v102, v102
	v_exp_f32_e32 v103, v103
	v_pk_mul_f32 v[118:119], v[118:119], v[4:5] op_sel_hi:[1,0]
	v_pk_mul_f32 v[116:117], v[116:117], v[4:5] op_sel_hi:[1,0]
	v_add_f32_e32 v100, 1.0, v100
	v_add_f32_e32 v101, 1.0, v101
	v_add_f32_e32 v102, 1.0, v102
	v_add_f32_e32 v103, 1.0, v103
	v_rcp_f32_e32 v100, v100
	v_rcp_f32_e32 v101, v101
	v_rcp_f32_e32 v102, v102
	v_rcp_f32_e32 v103, v103
	v_pk_mul_f32 v[118:119], v[28:29], v[118:119]
	v_pk_mul_f32 v[116:117], v[30:31], v[116:117]
	v_pk_mul_f32 v[118:119], v[118:119], v[92:93]
	v_pk_mul_f32 v[116:117], v[116:117], v[94:95]
	v_pk_mul_f32 v[118:119], v[100:101], v[118:119]
	v_pk_mul_f32 v[116:117], v[102:103], v[116:117]
	v_cvt_pk_bf16_f32 v118, v118, v119
	v_cvt_pk_bf16_f32 v119, v116, v117
	global_store_dwordx2 v[14:15], v[118:119], off
	s_waitcnt vmcnt(28)
	v_lshlrev_b32_e32 v92, 16, v22
	v_and_b32_e32 v93, 0xffff0000, v22
	v_lshlrev_b32_e32 v94, 16, v23
	v_and_b32_e32 v95, 0xffff0000, v23
	v_mul_f32_e32 v100, 0xbfb8aa3b, v92
	v_mul_f32_e32 v101, 0xbfb8aa3b, v93
	v_mul_f32_e32 v102, 0xbfb8aa3b, v94
	v_mul_f32_e32 v103, 0xbfb8aa3b, v95
	v_exp_f32_e32 v100, v100
	v_exp_f32_e32 v101, v101
	v_exp_f32_e32 v102, v102
	v_exp_f32_e32 v103, v103
	v_pk_mul_f32 v[114:115], v[114:115], v[4:5] op_sel_hi:[1,0]
	v_pk_mul_f32 v[112:113], v[112:113], v[4:5] op_sel_hi:[1,0]
	v_add_f32_e32 v100, 1.0, v100
	v_add_f32_e32 v101, 1.0, v101
	v_add_f32_e32 v102, 1.0, v102
	v_add_f32_e32 v103, 1.0, v103
	v_rcp_f32_e32 v100, v100
	v_rcp_f32_e32 v101, v101
	v_rcp_f32_e32 v102, v102
	v_rcp_f32_e32 v103, v103
	v_pk_mul_f32 v[114:115], v[120:121], v[114:115]
	v_pk_mul_f32 v[112:113], v[122:123], v[112:113]
	v_pk_mul_f32 v[114:115], v[114:115], v[92:93]
	v_pk_mul_f32 v[112:113], v[112:113], v[94:95]
	v_pk_mul_f32 v[114:115], v[100:101], v[114:115]
	v_pk_mul_f32 v[112:113], v[102:103], v[112:113]
	v_cvt_pk_bf16_f32 v114, v114, v115
	v_cvt_pk_bf16_f32 v115, v112, v113
	global_store_dwordx2 v[14:15], v[114:115], off offset:32
	s_waitcnt vmcnt(27)
	v_lshlrev_b32_e32 v92, 16, v24
	v_and_b32_e32 v93, 0xffff0000, v24
	v_lshlrev_b32_e32 v94, 16, v25
	v_and_b32_e32 v95, 0xffff0000, v25
	v_mul_f32_e32 v100, 0xbfb8aa3b, v92
	v_mul_f32_e32 v101, 0xbfb8aa3b, v93
	v_mul_f32_e32 v102, 0xbfb8aa3b, v94
	v_mul_f32_e32 v103, 0xbfb8aa3b, v95
	v_exp_f32_e32 v100, v100
	v_exp_f32_e32 v101, v101
	v_exp_f32_e32 v102, v102
	v_exp_f32_e32 v103, v103
	v_pk_mul_f32 v[106:107], v[106:107], v[4:5] op_sel_hi:[1,0]
	v_pk_mul_f32 v[104:105], v[104:105], v[4:5] op_sel_hi:[1,0]
	v_add_f32_e32 v100, 1.0, v100
	v_add_f32_e32 v101, 1.0, v101
	v_add_f32_e32 v102, 1.0, v102
	v_add_f32_e32 v103, 1.0, v103
	v_rcp_f32_e32 v100, v100
	v_rcp_f32_e32 v101, v101
	v_rcp_f32_e32 v102, v102
	v_rcp_f32_e32 v103, v103
	v_pk_mul_f32 v[106:107], v[124:125], v[106:107]
	v_pk_mul_f32 v[104:105], v[126:127], v[104:105]
	v_pk_mul_f32 v[106:107], v[106:107], v[92:93]
	v_pk_mul_f32 v[104:105], v[104:105], v[94:95]
	v_pk_mul_f32 v[106:107], v[100:101], v[106:107]
	v_pk_mul_f32 v[104:105], v[102:103], v[104:105]
	v_cvt_pk_bf16_f32 v106, v106, v107
	v_cvt_pk_bf16_f32 v107, v104, v105
	global_store_dwordx2 v[14:15], v[106:107], off offset:64
	s_waitcnt vmcnt(26)
	v_lshlrev_b32_e32 v92, 16, v26
	v_and_b32_e32 v93, 0xffff0000, v26
	v_lshlrev_b32_e32 v94, 16, v27
	v_and_b32_e32 v95, 0xffff0000, v27
	v_mul_f32_e32 v100, 0xbfb8aa3b, v92
	v_mul_f32_e32 v101, 0xbfb8aa3b, v93
	v_mul_f32_e32 v102, 0xbfb8aa3b, v94
	v_mul_f32_e32 v103, 0xbfb8aa3b, v95
	v_exp_f32_e32 v100, v100
	v_exp_f32_e32 v101, v101
	v_exp_f32_e32 v102, v102
	v_exp_f32_e32 v103, v103
	v_pk_mul_f32 v[98:99], v[98:99], v[4:5] op_sel_hi:[1,0]
	v_pk_mul_f32 v[96:97], v[96:97], v[4:5] op_sel_hi:[1,0]
	v_add_f32_e32 v100, 1.0, v100
	v_add_f32_e32 v101, 1.0, v101
	v_add_f32_e32 v102, 1.0, v102
	v_add_f32_e32 v103, 1.0, v103
	v_rcp_f32_e32 v100, v100
	v_rcp_f32_e32 v101, v101
	v_rcp_f32_e32 v102, v102
	v_rcp_f32_e32 v103, v103
	v_pk_mul_f32 v[98:99], v[128:129], v[98:99]
	v_pk_mul_f32 v[96:97], v[130:131], v[96:97]
	v_pk_mul_f32 v[98:99], v[98:99], v[92:93]
	v_pk_mul_f32 v[96:97], v[96:97], v[94:95]
	v_pk_mul_f32 v[98:99], v[100:101], v[98:99]
	v_pk_mul_f32 v[96:97], v[102:103], v[96:97]
	v_cvt_pk_bf16_f32 v98, v98, v99
	v_cvt_pk_bf16_f32 v99, v96, v97
	global_store_dwordx2 v[14:15], v[98:99], off offset:96
	s_waitcnt vmcnt(25)
	v_lshlrev_b32_e32 v92, 16, v34
	v_and_b32_e32 v93, 0xffff0000, v34
	v_lshlrev_b32_e32 v94, 16, v35
	v_and_b32_e32 v95, 0xffff0000, v35
	v_mul_f32_e32 v100, 0xbfb8aa3b, v92
	v_mul_f32_e32 v101, 0xbfb8aa3b, v93
	v_mul_f32_e32 v102, 0xbfb8aa3b, v94
	v_mul_f32_e32 v103, 0xbfb8aa3b, v95
	v_exp_f32_e32 v100, v100
	v_exp_f32_e32 v101, v101
	v_exp_f32_e32 v102, v102
	v_exp_f32_e32 v103, v103
	v_pk_mul_f32 v[90:91], v[90:91], v[4:5] op_sel_hi:[1,0]
	v_pk_mul_f32 v[88:89], v[88:89], v[4:5] op_sel_hi:[1,0]
	v_add_f32_e32 v100, 1.0, v100
	v_add_f32_e32 v101, 1.0, v101
	v_add_f32_e32 v102, 1.0, v102
	v_add_f32_e32 v103, 1.0, v103
	v_rcp_f32_e32 v100, v100
	v_rcp_f32_e32 v101, v101
	v_rcp_f32_e32 v102, v102
	v_rcp_f32_e32 v103, v103
	v_pk_mul_f32 v[90:91], v[132:133], v[90:91]
	v_pk_mul_f32 v[88:89], v[134:135], v[88:89]
	v_pk_mul_f32 v[90:91], v[90:91], v[92:93]
	v_pk_mul_f32 v[88:89], v[88:89], v[94:95]
	v_pk_mul_f32 v[90:91], v[100:101], v[90:91]
	v_pk_mul_f32 v[88:89], v[102:103], v[88:89]
	v_cvt_pk_bf16_f32 v90, v90, v91
	v_cvt_pk_bf16_f32 v91, v88, v89
	global_store_dwordx2 v[14:15], v[90:91], off offset:128
	s_waitcnt vmcnt(24)
	v_lshlrev_b32_e32 v92, 16, v46
	v_and_b32_e32 v93, 0xffff0000, v46
	v_lshlrev_b32_e32 v94, 16, v47
	v_and_b32_e32 v95, 0xffff0000, v47
	v_mul_f32_e32 v100, 0xbfb8aa3b, v92
	v_mul_f32_e32 v101, 0xbfb8aa3b, v93
	v_mul_f32_e32 v102, 0xbfb8aa3b, v94
	v_mul_f32_e32 v103, 0xbfb8aa3b, v95
	v_exp_f32_e32 v100, v100
	v_exp_f32_e32 v101, v101
	v_exp_f32_e32 v102, v102
	v_exp_f32_e32 v103, v103
	v_pk_mul_f32 v[82:83], v[82:83], v[4:5] op_sel_hi:[1,0]
	v_pk_mul_f32 v[80:81], v[80:81], v[4:5] op_sel_hi:[1,0]
	v_add_f32_e32 v100, 1.0, v100
	v_add_f32_e32 v101, 1.0, v101
	v_add_f32_e32 v102, 1.0, v102
	v_add_f32_e32 v103, 1.0, v103
	v_rcp_f32_e32 v100, v100
	v_rcp_f32_e32 v101, v101
	v_rcp_f32_e32 v102, v102
	v_rcp_f32_e32 v103, v103
	v_pk_mul_f32 v[82:83], v[136:137], v[82:83]
	v_pk_mul_f32 v[80:81], v[138:139], v[80:81]
	v_pk_mul_f32 v[82:83], v[82:83], v[92:93]
	v_pk_mul_f32 v[80:81], v[80:81], v[94:95]
	v_pk_mul_f32 v[82:83], v[100:101], v[82:83]
	v_pk_mul_f32 v[80:81], v[102:103], v[80:81]
	v_cvt_pk_bf16_f32 v82, v82, v83
	v_cvt_pk_bf16_f32 v83, v80, v81
	global_store_dwordx2 v[14:15], v[82:83], off offset:160
	s_waitcnt vmcnt(23)
	v_lshlrev_b32_e32 v92, 16, v52
	v_and_b32_e32 v93, 0xffff0000, v52
	v_lshlrev_b32_e32 v94, 16, v53
	v_and_b32_e32 v95, 0xffff0000, v53
	v_mul_f32_e32 v100, 0xbfb8aa3b, v92
	v_mul_f32_e32 v101, 0xbfb8aa3b, v93
	v_mul_f32_e32 v102, 0xbfb8aa3b, v94
	v_mul_f32_e32 v103, 0xbfb8aa3b, v95
	v_exp_f32_e32 v100, v100
	v_exp_f32_e32 v101, v101
	v_exp_f32_e32 v102, v102
	v_exp_f32_e32 v103, v103
	v_pk_mul_f32 v[74:75], v[74:75], v[4:5] op_sel_hi:[1,0]
	v_pk_mul_f32 v[72:73], v[72:73], v[4:5] op_sel_hi:[1,0]
	v_add_f32_e32 v100, 1.0, v100
	v_add_f32_e32 v101, 1.0, v101
	v_add_f32_e32 v102, 1.0, v102
	v_add_f32_e32 v103, 1.0, v103
	v_rcp_f32_e32 v100, v100
	v_rcp_f32_e32 v101, v101
	v_rcp_f32_e32 v102, v102
	v_rcp_f32_e32 v103, v103
	v_pk_mul_f32 v[74:75], v[140:141], v[74:75]
	v_pk_mul_f32 v[72:73], v[142:143], v[72:73]
	v_pk_mul_f32 v[74:75], v[74:75], v[92:93]
	v_pk_mul_f32 v[72:73], v[72:73], v[94:95]
	v_pk_mul_f32 v[74:75], v[100:101], v[74:75]
	v_pk_mul_f32 v[72:73], v[102:103], v[72:73]
	v_cvt_pk_bf16_f32 v74, v74, v75
	v_cvt_pk_bf16_f32 v75, v72, v73
	global_store_dwordx2 v[14:15], v[74:75], off offset:192
	s_waitcnt vmcnt(22)
	v_lshlrev_b32_e32 v92, 16, v54
	v_and_b32_e32 v93, 0xffff0000, v54
	v_lshlrev_b32_e32 v94, 16, v55
	v_and_b32_e32 v95, 0xffff0000, v55
	v_mul_f32_e32 v100, 0xbfb8aa3b, v92
	v_mul_f32_e32 v101, 0xbfb8aa3b, v93
	v_mul_f32_e32 v102, 0xbfb8aa3b, v94
	v_mul_f32_e32 v103, 0xbfb8aa3b, v95
	v_exp_f32_e32 v100, v100
	v_exp_f32_e32 v101, v101
	v_exp_f32_e32 v102, v102
	v_exp_f32_e32 v103, v103
	v_pk_mul_f32 v[66:67], v[66:67], v[4:5] op_sel_hi:[1,0]
	v_pk_mul_f32 v[64:65], v[64:65], v[4:5] op_sel_hi:[1,0]
	v_add_f32_e32 v100, 1.0, v100
	v_add_f32_e32 v101, 1.0, v101
	v_add_f32_e32 v102, 1.0, v102
	v_add_f32_e32 v103, 1.0, v103
	v_rcp_f32_e32 v100, v100
	v_rcp_f32_e32 v101, v101
	v_rcp_f32_e32 v102, v102
	v_rcp_f32_e32 v103, v103
	v_pk_mul_f32 v[66:67], v[196:197], v[66:67]
	v_pk_mul_f32 v[64:65], v[198:199], v[64:65]
	v_pk_mul_f32 v[66:67], v[66:67], v[92:93]
	v_pk_mul_f32 v[64:65], v[64:65], v[94:95]
	v_pk_mul_f32 v[66:67], v[100:101], v[66:67]
	v_pk_mul_f32 v[64:65], v[102:103], v[64:65]
	v_cvt_pk_bf16_f32 v66, v66, v67
	v_cvt_pk_bf16_f32 v67, v64, v65
	global_store_dwordx2 v[14:15], v[66:67], off offset:224
	s_waitcnt vmcnt(21)
	v_lshlrev_b32_e32 v92, 16, v60
	v_and_b32_e32 v93, 0xffff0000, v60
	v_lshlrev_b32_e32 v94, 16, v61
	v_and_b32_e32 v95, 0xffff0000, v61
	v_mul_f32_e32 v100, 0xbfb8aa3b, v92
	v_mul_f32_e32 v101, 0xbfb8aa3b, v93
	v_mul_f32_e32 v102, 0xbfb8aa3b, v94
	v_mul_f32_e32 v103, 0xbfb8aa3b, v95
	v_exp_f32_e32 v100, v100
	v_exp_f32_e32 v101, v101
	v_exp_f32_e32 v102, v102
	v_exp_f32_e32 v103, v103
	v_pk_mul_f32 v[58:59], v[58:59], v[4:5] op_sel_hi:[1,0]
	v_pk_mul_f32 v[56:57], v[56:57], v[4:5] op_sel_hi:[1,0]
	v_add_f32_e32 v100, 1.0, v100
	v_add_f32_e32 v101, 1.0, v101
	v_add_f32_e32 v102, 1.0, v102
	v_add_f32_e32 v103, 1.0, v103
	v_rcp_f32_e32 v100, v100
	v_rcp_f32_e32 v101, v101
	v_rcp_f32_e32 v102, v102
	v_rcp_f32_e32 v103, v103
	v_pk_mul_f32 v[58:59], v[200:201], v[58:59]
	v_pk_mul_f32 v[56:57], v[202:203], v[56:57]
	v_pk_mul_f32 v[58:59], v[58:59], v[92:93]
	v_pk_mul_f32 v[56:57], v[56:57], v[94:95]
	v_pk_mul_f32 v[58:59], v[100:101], v[58:59]
	v_pk_mul_f32 v[56:57], v[102:103], v[56:57]
	v_cvt_pk_bf16_f32 v58, v58, v59
	v_cvt_pk_bf16_f32 v59, v56, v57
	global_store_dwordx2 v[14:15], v[58:59], off offset:256
	s_waitcnt vmcnt(20)
	v_lshlrev_b32_e32 v92, 16, v62
	v_and_b32_e32 v93, 0xffff0000, v62
	v_lshlrev_b32_e32 v94, 16, v63
	v_and_b32_e32 v95, 0xffff0000, v63
	v_mul_f32_e32 v100, 0xbfb8aa3b, v92
	v_mul_f32_e32 v101, 0xbfb8aa3b, v93
	v_mul_f32_e32 v102, 0xbfb8aa3b, v94
	v_mul_f32_e32 v103, 0xbfb8aa3b, v95
	v_exp_f32_e32 v100, v100
	v_exp_f32_e32 v101, v101
	v_exp_f32_e32 v102, v102
	v_exp_f32_e32 v103, v103
	v_pk_mul_f32 v[48:49], v[48:49], v[4:5] op_sel_hi:[1,0]
	v_pk_mul_f32 v[50:51], v[50:51], v[4:5] op_sel_hi:[1,0]
	v_add_f32_e32 v100, 1.0, v100
	v_add_f32_e32 v101, 1.0, v101
	v_add_f32_e32 v102, 1.0, v102
	v_add_f32_e32 v103, 1.0, v103
	v_rcp_f32_e32 v100, v100
	v_rcp_f32_e32 v101, v101
	v_rcp_f32_e32 v102, v102
	v_rcp_f32_e32 v103, v103
	v_pk_mul_f32 v[48:49], v[204:205], v[48:49]
	v_pk_mul_f32 v[50:51], v[206:207], v[50:51]
	v_pk_mul_f32 v[48:49], v[48:49], v[92:93]
	v_pk_mul_f32 v[50:51], v[50:51], v[94:95]
	v_pk_mul_f32 v[48:49], v[100:101], v[48:49]
	v_pk_mul_f32 v[50:51], v[102:103], v[50:51]
	v_cvt_pk_bf16_f32 v48, v48, v49
	v_cvt_pk_bf16_f32 v49, v50, v51
	global_store_dwordx2 v[14:15], v[48:49], off offset:288
	s_waitcnt vmcnt(19)
	v_lshlrev_b32_e32 v92, 16, v68
	v_and_b32_e32 v93, 0xffff0000, v68
	v_lshlrev_b32_e32 v94, 16, v69
	v_and_b32_e32 v95, 0xffff0000, v69
	v_mul_f32_e32 v100, 0xbfb8aa3b, v92
	v_mul_f32_e32 v101, 0xbfb8aa3b, v93
	v_mul_f32_e32 v102, 0xbfb8aa3b, v94
	v_mul_f32_e32 v103, 0xbfb8aa3b, v95
	v_exp_f32_e32 v100, v100
	v_exp_f32_e32 v101, v101
	v_exp_f32_e32 v102, v102
	v_exp_f32_e32 v103, v103
	v_pk_mul_f32 v[42:43], v[42:43], v[4:5] op_sel_hi:[1,0]
	v_pk_mul_f32 v[40:41], v[40:41], v[4:5] op_sel_hi:[1,0]
	v_add_f32_e32 v100, 1.0, v100
	v_add_f32_e32 v101, 1.0, v101
	v_add_f32_e32 v102, 1.0, v102
	v_add_f32_e32 v103, 1.0, v103
	v_rcp_f32_e32 v100, v100
	v_rcp_f32_e32 v101, v101
	v_rcp_f32_e32 v102, v102
	v_rcp_f32_e32 v103, v103
	v_pk_mul_f32 v[42:43], v[208:209], v[42:43]
	v_pk_mul_f32 v[40:41], v[210:211], v[40:41]
	v_pk_mul_f32 v[42:43], v[42:43], v[92:93]
	v_pk_mul_f32 v[40:41], v[40:41], v[94:95]
	v_pk_mul_f32 v[42:43], v[100:101], v[42:43]
	v_pk_mul_f32 v[40:41], v[102:103], v[40:41]
	v_cvt_pk_bf16_f32 v42, v42, v43
	v_cvt_pk_bf16_f32 v43, v40, v41
	global_store_dwordx2 v[14:15], v[42:43], off offset:320
	s_waitcnt vmcnt(18)
	v_lshlrev_b32_e32 v92, 16, v70
	v_and_b32_e32 v93, 0xffff0000, v70
	v_lshlrev_b32_e32 v94, 16, v71
	v_and_b32_e32 v95, 0xffff0000, v71
	v_mul_f32_e32 v100, 0xbfb8aa3b, v92
	v_mul_f32_e32 v101, 0xbfb8aa3b, v93
	v_mul_f32_e32 v102, 0xbfb8aa3b, v94
	v_mul_f32_e32 v103, 0xbfb8aa3b, v95
	v_exp_f32_e32 v100, v100
	v_exp_f32_e32 v101, v101
	v_exp_f32_e32 v102, v102
	v_exp_f32_e32 v103, v103
	v_pk_mul_f32 v[38:39], v[38:39], v[4:5] op_sel_hi:[1,0]
	v_pk_mul_f32 v[36:37], v[36:37], v[4:5] op_sel_hi:[1,0]
	v_add_f32_e32 v100, 1.0, v100
	v_add_f32_e32 v101, 1.0, v101
	v_add_f32_e32 v102, 1.0, v102
	v_add_f32_e32 v103, 1.0, v103
	v_rcp_f32_e32 v100, v100
	v_rcp_f32_e32 v101, v101
	v_rcp_f32_e32 v102, v102
	v_rcp_f32_e32 v103, v103
	v_pk_mul_f32 v[38:39], v[212:213], v[38:39]
	v_pk_mul_f32 v[36:37], v[214:215], v[36:37]
	v_pk_mul_f32 v[38:39], v[38:39], v[92:93]
	v_pk_mul_f32 v[36:37], v[36:37], v[94:95]
	v_pk_mul_f32 v[38:39], v[100:101], v[38:39]
	v_pk_mul_f32 v[36:37], v[102:103], v[36:37]
	v_cvt_pk_bf16_f32 v38, v38, v39
	v_cvt_pk_bf16_f32 v39, v36, v37
	global_store_dwordx2 v[14:15], v[38:39], off offset:352
	s_waitcnt vmcnt(17)
	v_lshlrev_b32_e32 v92, 16, v76
	v_and_b32_e32 v93, 0xffff0000, v76
	v_lshlrev_b32_e32 v94, 16, v77
	v_and_b32_e32 v95, 0xffff0000, v77
	v_mul_f32_e32 v100, 0xbfb8aa3b, v92
	v_mul_f32_e32 v101, 0xbfb8aa3b, v93
	v_mul_f32_e32 v102, 0xbfb8aa3b, v94
	v_mul_f32_e32 v103, 0xbfb8aa3b, v95
	v_exp_f32_e32 v100, v100
	v_exp_f32_e32 v101, v101
	v_exp_f32_e32 v102, v102
	v_exp_f32_e32 v103, v103
	v_pk_mul_f32 v[32:33], v[32:33], v[4:5] op_sel_hi:[1,0]
	v_pk_mul_f32 v[18:19], v[18:19], v[4:5] op_sel_hi:[1,0]
	v_add_f32_e32 v100, 1.0, v100
	v_add_f32_e32 v101, 1.0, v101
	v_add_f32_e32 v102, 1.0, v102
	v_add_f32_e32 v103, 1.0, v103
	v_rcp_f32_e32 v100, v100
	v_rcp_f32_e32 v101, v101
	v_rcp_f32_e32 v102, v102
	v_rcp_f32_e32 v103, v103
	v_pk_mul_f32 v[32:33], v[216:217], v[32:33]
	v_pk_mul_f32 v[18:19], v[218:219], v[18:19]
	v_pk_mul_f32 v[32:33], v[32:33], v[92:93]
	v_pk_mul_f32 v[18:19], v[18:19], v[94:95]
	v_pk_mul_f32 v[32:33], v[100:101], v[32:33]
	v_pk_mul_f32 v[18:19], v[102:103], v[18:19]
	v_cvt_pk_bf16_f32 v32, v32, v33
	v_cvt_pk_bf16_f32 v33, v18, v19
	global_store_dwordx2 v[14:15], v[32:33], off offset:384
	s_waitcnt vmcnt(16)
	v_lshlrev_b32_e32 v92, 16, v78
	v_and_b32_e32 v93, 0xffff0000, v78
	v_lshlrev_b32_e32 v94, 16, v79
	v_and_b32_e32 v95, 0xffff0000, v79
	v_mul_f32_e32 v100, 0xbfb8aa3b, v92
	v_mul_f32_e32 v101, 0xbfb8aa3b, v93
	v_mul_f32_e32 v102, 0xbfb8aa3b, v94
	v_mul_f32_e32 v103, 0xbfb8aa3b, v95
	v_exp_f32_e32 v100, v100
	v_exp_f32_e32 v101, v101
	v_exp_f32_e32 v102, v102
	v_exp_f32_e32 v103, v103
	v_pk_mul_f32 v[16:17], v[16:17], v[4:5] op_sel_hi:[1,0]
	v_pk_mul_f32 v[10:11], v[10:11], v[4:5] op_sel_hi:[1,0]
	v_add_f32_e32 v100, 1.0, v100
	v_add_f32_e32 v101, 1.0, v101
	v_add_f32_e32 v102, 1.0, v102
	v_add_f32_e32 v103, 1.0, v103
	v_rcp_f32_e32 v100, v100
	v_rcp_f32_e32 v101, v101
	v_rcp_f32_e32 v102, v102
	v_rcp_f32_e32 v103, v103
	v_pk_mul_f32 v[16:17], v[220:221], v[16:17]
	v_pk_mul_f32 v[10:11], v[222:223], v[10:11]
	v_pk_mul_f32 v[16:17], v[16:17], v[92:93]
	v_pk_mul_f32 v[10:11], v[10:11], v[94:95]
	v_pk_mul_f32 v[16:17], v[100:101], v[16:17]
	v_pk_mul_f32 v[10:11], v[102:103], v[10:11]
	v_cvt_pk_bf16_f32 v16, v16, v17
	v_cvt_pk_bf16_f32 v17, v10, v11
	global_store_dwordx2 v[14:15], v[16:17], off offset:416
	s_waitcnt vmcnt(15)
	v_lshlrev_b32_e32 v92, 16, v84
	v_and_b32_e32 v93, 0xffff0000, v84
	v_lshlrev_b32_e32 v94, 16, v85
	v_and_b32_e32 v95, 0xffff0000, v85
	v_mul_f32_e32 v100, 0xbfb8aa3b, v92
	v_mul_f32_e32 v101, 0xbfb8aa3b, v93
	v_mul_f32_e32 v102, 0xbfb8aa3b, v94
	v_mul_f32_e32 v103, 0xbfb8aa3b, v95
	v_exp_f32_e32 v100, v100
	v_exp_f32_e32 v101, v101
	v_exp_f32_e32 v102, v102
	v_exp_f32_e32 v103, v103
	v_pk_mul_f32 v[8:9], v[8:9], v[4:5] op_sel_hi:[1,0]
	v_pk_mul_f32 v[6:7], v[6:7], v[4:5] op_sel_hi:[1,0]
	v_add_f32_e32 v100, 1.0, v100
	v_add_f32_e32 v101, 1.0, v101
	v_add_f32_e32 v102, 1.0, v102
	v_add_f32_e32 v103, 1.0, v103
	v_rcp_f32_e32 v100, v100
	v_rcp_f32_e32 v101, v101
	v_rcp_f32_e32 v102, v102
	v_rcp_f32_e32 v103, v103
	v_pk_mul_f32 v[8:9], v[224:225], v[8:9]
	v_pk_mul_f32 v[6:7], v[226:227], v[6:7]
	v_pk_mul_f32 v[8:9], v[8:9], v[92:93]
	v_pk_mul_f32 v[6:7], v[6:7], v[94:95]
	v_pk_mul_f32 v[8:9], v[100:101], v[8:9]
	v_pk_mul_f32 v[6:7], v[102:103], v[6:7]
	v_cvt_pk_bf16_f32 v8, v8, v9
	v_cvt_pk_bf16_f32 v9, v6, v7
	global_store_dwordx2 v[14:15], v[8:9], off offset:448
	s_waitcnt vmcnt(15)
	v_lshlrev_b32_e32 v92, 16, v20
	v_and_b32_e32 v93, 0xffff0000, v20
	v_lshlrev_b32_e32 v94, 16, v21
	v_and_b32_e32 v95, 0xffff0000, v21
	v_mul_f32_e32 v100, 0xbfb8aa3b, v92
	v_mul_f32_e32 v101, 0xbfb8aa3b, v93
	v_mul_f32_e32 v102, 0xbfb8aa3b, v94
	v_mul_f32_e32 v103, 0xbfb8aa3b, v95
	v_exp_f32_e32 v100, v100
	v_exp_f32_e32 v101, v101
	v_exp_f32_e32 v102, v102
	v_exp_f32_e32 v103, v103
	v_pk_mul_f32 v[0:1], v[0:1], v[4:5] op_sel_hi:[1,0]
	v_pk_mul_f32 v[2:3], v[2:3], v[4:5] op_sel_hi:[1,0]
	v_add_f32_e32 v100, 1.0, v100
	v_add_f32_e32 v101, 1.0, v101
	v_add_f32_e32 v102, 1.0, v102
	v_add_f32_e32 v103, 1.0, v103
	v_rcp_f32_e32 v100, v100
	v_rcp_f32_e32 v101, v101
	v_rcp_f32_e32 v102, v102
	v_rcp_f32_e32 v103, v103
	v_pk_mul_f32 v[0:1], v[228:229], v[0:1]
	v_pk_mul_f32 v[2:3], v[230:231], v[2:3]
	v_pk_mul_f32 v[0:1], v[0:1], v[92:93]
	v_pk_mul_f32 v[2:3], v[2:3], v[94:95]
	v_pk_mul_f32 v[0:1], v[100:101], v[0:1]
	v_pk_mul_f32 v[2:3], v[102:103], v[2:3]
	v_cvt_pk_bf16_f32 v0, v0, v1
	v_cvt_pk_bf16_f32 v1, v2, v3
	global_store_dwordx2 v[14:15], v[0:1], off offset:480

.LBB0_229:
	s_or_b64 exec, exec, s[0:1]
	s_waitcnt lgkmcnt(0)
	s_barrier
	ds_read_b32 v0, v181
	s_mov_b64 s[0:1], -1
	s_waitcnt lgkmcnt(0)
	v_cmp_lt_i32_e32 vcc, s25, v0
	v_readfirstlane_b32 s4, v0
	s_cbranch_vccnz .LBB0_224
	s_ashr_i32 s0, s4, 31
	s_lshr_b32 s0, s0, 23
	s_add_i32 s0, s4, s0
	s_and_b32 s0, s0, 0xfffffe00
	s_sub_i32 s6, s4, s0
	v_readfirstlane_b32 s0, v183
	s_ashr_i32 s7, s6, 5
	s_lshr_b32 s0, s0, 2
	s_sub_i32 s8, 15, s7
	s_and_b32 s9, s0, 0x3ffffff0
	s_lshl_b32 s0, s6, 8
	s_and_b32 s4, s6, 7
	s_lshl_b32 s5, s8, 7
	s_and_b32 s16, s0, 0x1800
	s_add_i32 s37, s9, s5
	s_add_i32 s10, s4, 1
	s_mul_i32 s0, s16, 0xc000
	s_add_u32 s0, s74, s0
	s_addc_u32 s1, s75, 0
	s_lshl_b32 s36, s4, 8
	s_mul_i32 s11, s8, 0x600000
	s_mul_hi_u32 s5, s5, 0xc000
	s_add_u32 s11, s0, s11
	s_addc_u32 s5, s1, s5
	s_lshl_b32 s4, s4, 9
	s_add_u32 s4, s11, s4
	s_addc_u32 s5, s5, 0
	v_mov_b32_e32 v149, v145
	v_lshl_add_u64 v[0:1], s[4:5], 0, v[148:149]
	v_lshl_add_u64 v[28:29], v[0:1], 0, s[18:19]
	v_mov_b32_e32 v151, v145
	v_lshl_add_u64 v[24:25], v[28:29], 0, v[150:151]
	v_add_co_u32_e32 v8, vcc, s27, v24
	v_mov_b32_e32 v153, v145
	s_nop 0
	v_addc_co_u32_e32 v9, vcc, 0, v25, vcc
	v_add_co_u32_e32 v16, vcc, s28, v24
	v_or_b32_e32 v33, s36, v174
	s_waitcnt lgkmcnt(0)
	s_barrier
	v_lshl_add_u64 v[4:5], v[28:29], 0, v[152:153]
	v_addc_co_u32_e32 v17, vcc, 0, v25, vcc
	global_load_dwordx4 v[0:3], v[24:25], off
	s_nop 0
	global_load_dwordx4 v[4:7], v[4:5], off
	v_add_co_u32_e32 v24, vcc, s29, v24
	v_lshlrev_b32_e32 v162, 1, v33
	v_mov_b32_e32 v163, v145
	v_or_b32_e32 v32, s36, v173
	v_mov_b32_e32 v155, v145
	v_mov_b32_e32 v157, v145
	v_addc_co_u32_e32 v25, vcc, 0, v25, vcc
	v_mov_b32_e32 v159, v145
	v_lshl_add_u64 v[48:49], s[0:1], 0, v[162:163]
	v_lshl_add_u64 v[12:13], v[28:29], 0, v[154:155]
	v_lshl_add_u64 v[20:21], v[28:29], 0, v[156:157]
	v_lshl_add_u64 v[28:29], v[28:29], 0, v[158:159]
	v_lshlrev_b32_e32 v144, 1, v32
	v_add_co_u32_e32 v44, vcc, s30, v48
	global_load_dwordx4 v[8:11], v[8:9], off
	s_nop 0
	global_load_dwordx4 v[12:15], v[12:13], off
	s_nop 0
	global_load_dwordx4 v[16:19], v[16:17], off
	s_nop 0
	global_load_dwordx4 v[20:23], v[20:21], off
	v_addc_co_u32_e32 v45, vcc, 0, v49, vcc
	global_load_dwordx4 v[24:27], v[24:25], off
	v_lshl_add_u64 v[50:51], s[0:1], 0, v[144:145]
	global_load_dwordx4 v[28:31], v[28:29], off
	s_nop 0
	global_load_dwordx4 v[32:35], v144, s[0:1]
	global_load_dwordx4 v[36:39], v144, s[0:1] offset:256
	s_lshl_b32 s38, s8, 2
	v_add_co_u32_e32 v50, vcc, s27, v50
	s_add_i32 s38, s38, 4
	global_load_dwordx4 v[40:43], v162, s[0:1]
	v_addc_co_u32_e32 v51, vcc, 0, v51, vcc
	global_load_dwordx4 v[44:47], v[44:45], off
	s_add_u32 s0, s0, 0x180000
	v_add_co_u32_e32 v48, vcc, s31, v48
	s_addc_u32 s1, s1, 0
	s_nop 0
	v_addc_co_u32_e32 v49, vcc, 0, v49, vcc
	global_load_dwordx4 v[116:119], v[50:51], off offset:256
	global_load_dwordx4 v[132:135], v[48:49], off
	global_load_dwordx4 v[124:127], v144, s[0:1]
	global_load_dwordx4 v[140:143], v162, s[0:1]
	v_cvt_f32_ubyte0_e32 v48, s10
	s_bfe_u32 s0, s6, 0x20003
	v_exp_f32_e64 v48, -v48
	s_or_b32 s41, s37, 15
	s_mul_i32 s0, s0, 0x6000000
	s_add_u32 s22, s70, s0
	s_addc_u32 s23, s71, 0
	s_lshl_b32 s0, s7, 2
	s_sub_i32 s42, s0, 64
	s_lshl_b32 s0, s7, 7
	v_mul_f32_e32 v149, 0x3fb8aa3b, v48
	s_mov_b32 s39, 31
	s_mov_b32 s40, 2
	v_mul_f32_e32 v151, 0x41800000, v149
	s_waitcnt vmcnt(15)
	ds_write_b128 v184, v[0:3]
	s_waitcnt vmcnt(14)
	ds_write_b128 v185, v[4:7]
	s_waitcnt vmcnt(13)
	ds_write_b128 v184, v[8:11] offset:8704
	s_waitcnt vmcnt(12)
	ds_write_b128 v186, v[12:15]
	s_waitcnt vmcnt(11)
	ds_write_b128 v184, v[16:19] offset:17408
	s_waitcnt vmcnt(10)
	ds_write_b128 v187, v[20:23]
	s_waitcnt vmcnt(9)
	ds_write_b128 v184, v[24:27] offset:26112
	s_waitcnt vmcnt(8)
	ds_write_b128 v188, v[28:31]
	s_waitcnt vmcnt(7)
	ds_write_b128 v189, v[32:35]
	s_waitcnt vmcnt(6)
	ds_write_b128 v189, v[36:39] offset:8704
	s_waitcnt vmcnt(5)
	ds_write_b128 v190, v[40:43] offset:17408
	s_waitcnt vmcnt(4)
	ds_write_b128 v190, v[44:47] offset:26112
	v_or_b32_e32 v0, s9, v169
	s_waitcnt lgkmcnt(0)
	s_barrier
	v_mul_lo_u32 v0, v0, s3
	v_add_u32_e32 v1, s9, v180
	v_mov_b32_e32 v40, v145
	v_mov_b32_e32 v41, v145
	v_mov_b32_e32 v42, v145
	v_mov_b32_e32 v43, v145
	v_subrev_u32_e32 v194, s0, v1
	v_add_u32_e32 v195, v177, v0
	v_mov_b64_e32 v[58:59], v[42:43]
	v_mov_b64_e32 v[66:67], v[42:43]
	v_mov_b64_e32 v[74:75], v[42:43]
	v_mov_b64_e32 v[82:83], v[42:43]
	v_mov_b64_e32 v[90:91], v[42:43]
	v_mov_b64_e32 v[98:99], v[42:43]
	v_mov_b64_e32 v[106:107], v[42:43]
	v_mov_b64_e32 v[114:115], v[42:43]
	v_mov_b64_e32 v[130:131], v[42:43]
	v_mov_b64_e32 v[0:1], v[40:41]
	v_mov_b64_e32 v[4:5], v[40:41]
	v_mov_b64_e32 v[8:9], v[40:41]
	v_mov_b64_e32 v[16:17], v[40:41]
	v_mov_b64_e32 v[28:29], v[40:41]
	v_mov_b64_e32 v[46:47], v[42:43]
	v_mov_b64_e32 v[50:51], v[42:43]
	v_mov_b64_e32 v[62:63], v[42:43]
	v_mov_b64_e32 v[70:71], v[42:43]
	v_mov_b64_e32 v[78:79], v[42:43]
	v_mov_b64_e32 v[86:87], v[42:43]
	v_mov_b64_e32 v[94:95], v[42:43]
	v_mov_b64_e32 v[102:103], v[42:43]
	v_mov_b64_e32 v[110:111], v[42:43]
	v_mov_b64_e32 v[122:123], v[42:43]
	v_mov_b64_e32 v[138:139], v[42:43]
	v_mov_b64_e32 v[54:55], v[42:43]
	v_mov_b64_e32 v[36:37], v[40:41]
	v_mov_b64_e32 v[32:33], v[40:41]
	v_mov_b64_e32 v[24:25], v[40:41]
	v_mov_b64_e32 v[20:21], v[40:41]
	v_mov_b64_e32 v[12:13], v[40:41]
	v_mul_f32_e32 v153, 0, v149
	v_add_f32_e32 v155, v149, v149
	v_mul_f32_e32 v157, 0x40400000, v149
	v_mul_f32_e32 v159, 0x41880000, v149
	v_mul_f32_e32 v161, 0x41900000, v149
	v_mul_f32_e32 v193, 0x41980000, v149
	v_mov_b32_e32 v164, v145
	v_mov_b32_e32 v165, v145
	v_mov_b32_e32 v166, 0xf149f2ca
	v_mov_b64_e32 v[56:57], v[40:41]
	v_mov_b64_e32 v[64:65], v[40:41]
	v_mov_b64_e32 v[72:73], v[40:41]
	v_mov_b64_e32 v[80:81], v[40:41]
	v_mov_b64_e32 v[88:89], v[40:41]
	v_mov_b64_e32 v[96:97], v[40:41]
	v_mov_b64_e32 v[104:105], v[40:41]
	v_mov_b64_e32 v[112:113], v[40:41]
	v_mov_b64_e32 v[128:129], v[40:41]
	v_mov_b64_e32 v[2:3], v[42:43]
	v_mov_b64_e32 v[6:7], v[42:43]
	v_mov_b64_e32 v[10:11], v[42:43]
	v_mov_b64_e32 v[18:19], v[42:43]
	v_mov_b64_e32 v[30:31], v[42:43]
	v_mov_b64_e32 v[44:45], v[40:41]
	v_mov_b64_e32 v[48:49], v[40:41]
	v_mov_b64_e32 v[60:61], v[40:41]
	v_mov_b64_e32 v[68:69], v[40:41]
	v_mov_b64_e32 v[76:77], v[40:41]
	v_mov_b64_e32 v[84:85], v[40:41]
	v_mov_b64_e32 v[92:93], v[40:41]
	v_mov_b64_e32 v[100:101], v[40:41]
	v_mov_b64_e32 v[108:109], v[40:41]
	v_mov_b64_e32 v[120:121], v[40:41]
	v_mov_b64_e32 v[136:137], v[40:41]
	v_mov_b32_e32 v167, 0xf149f2ca
	v_mov_b64_e32 v[52:53], v[40:41]
	v_mov_b64_e32 v[38:39], v[42:43]
	v_mov_b64_e32 v[34:35], v[42:43]
	v_mov_b64_e32 v[26:27], v[42:43]
	v_mov_b64_e32 v[22:23], v[42:43]
	v_mov_b64_e32 v[14:15], v[42:43]
	v_readfirstlane_b32 s86, v149
	v_readfirstlane_b32 s87, v151
	v_readfirstlane_b32 s88, v155
	v_readfirstlane_b32 s89, v157
	v_readfirstlane_b32 s90, v159
	ds_read_b128 v[240:243], v195
	ds_read_b128 v[244:247], v195 offset:64
	ds_read_b128 v[248:251], v195 offset:128
	ds_read_b128 v[252:255], v195 offset:192
	ds_read_b128 v[148:151], v195 offset:34816
	ds_read_b128 v[152:155], v195 offset:34880
	ds_read_b128 v[156:159], v195 offset:34944
	ds_read_b128 v[184:187], v195 offset:35008
	s_waitcnt lgkmcnt(0)

.Latt_top_done:
	s_sub_i32 s0, s39, 31
	s_cmp_gt_u32 s0, s41
	s_cbranch_scc1 .LBB0_235
	s_cmp_gt_u32 s39, s37
	s_cbranch_scc1 .Latt_diag
	v_add_u32_e32 v168, s43, v178
	ds_read_b128 v[196:199], v168
	ds_read_b128 v[208:211], v168 offset:64
	ds_read_b128 v[212:215], v168 offset:4352
	ds_read_b128 v[216:219], v168 offset:4416
	v_cvt_f32_i32_e32 v224, v194
	s_waitcnt lgkmcnt(3)
	v_mfma_f32_16x16x32_bf16 v[196:199], v[196:199], v[240:243], 0
	s_waitcnt lgkmcnt(1)
	v_mfma_f32_16x16x32_bf16 v[200:203], v[212:215], v[240:243], 0
	ds_read_b128 v[212:215], v168 offset:128
	v_mfma_f32_16x16x32_bf16 v[196:199], v[208:211], v[244:247], v[196:199]
	ds_read_b128 v[220:223], v168 offset:192
	s_waitcnt lgkmcnt(2)
	v_mfma_f32_16x16x32_bf16 v[200:203], v[216:219], v[244:247], v[200:203]
	ds_read_b128 v[216:219], v168 offset:4480
	s_waitcnt lgkmcnt(2)
	v_mfma_f32_16x16x32_bf16 v[196:199], v[212:215], v[248:251], v[196:199]
	ds_read_b128 v[212:215], v168 offset:4544
	s_waitcnt lgkmcnt(1)
	v_mfma_f32_16x16x32_bf16 v[200:203], v[216:219], v[248:251], v[200:203]
	v_mfma_f32_16x16x32_bf16 v[220:223], v[220:223], v[252:255], v[196:199]
	s_waitcnt lgkmcnt(0)
	v_mfma_f32_16x16x32_bf16 v[202:205], v[212:215], v[252:255], v[200:203]
	ds_read_b128 v[206:209], v168 offset:8704
	ds_read_b128 v[214:217], v168 offset:13056
	v_mul_f32_e64 v197, -s86, v224
	s_nop 1
	s_nop 0
	v_fmamk_f32 v196, v220, 0x3e0293ee, v197
	v_add_f32_e32 v198, 0, v196
	v_fmamk_f32 v196, v221, 0x3e0293ee, v197
	v_fmamk_f32 v200, v222, 0x3e0293ee, v197
	v_fmamk_f32 v201, v223, 0x3e0293ee, v197
	ds_read_b128 v[222:225], v168 offset:8768
	s_waitcnt lgkmcnt(2)
	v_mfma_f32_16x16x32_bf16 v[206:209], v[206:209], v[148:151], 0
	ds_read_b128 v[226:229], v168 offset:13120
	v_add_f32_e32 v199, s86, v196
	s_waitcnt lgkmcnt(2)
	v_mfma_f32_16x16x32_bf16 v[210:213], v[214:217], v[148:151], 0
	ds_read_b128 v[214:217], v168 offset:8832
	v_add_f32_e32 v200, s88, v200
	v_add_f32_e32 v201, s89, v201
	s_waitcnt lgkmcnt(2)
	v_mfma_f32_16x16x32_bf16 v[206:209], v[222:225], v[152:155], v[206:209]
	ds_read_b128 v[230:233], v168 offset:13184
	v_fmamk_f32 v202, v202, 0x3e0293ee, v197
	v_fmamk_f32 v203, v203, 0x3e0293ee, v197
	v_max3_f32 v196, v198, s33, v199
	v_add_f32_e32 v202, s87, v202
	v_add_f32_e32 v203, s90, v203
	v_fmamk_f32 v204, v204, 0x3e0293ee, v197
	v_fmamk_f32 v205, v205, 0x3e0293ee, v197
	v_max3_f32 v196, v196, v200, v201
	v_add_f32_e32 v204, v161, v204
	v_add_f32_e32 v205, v193, v205
	s_waitcnt lgkmcnt(2)
	v_mfma_f32_16x16x32_bf16 v[210:213], v[226:229], v[152:155], v[210:213]
	ds_read_b128 v[226:229], v168 offset:8896
	v_max3_f32 v196, v196, v202, v203
	s_waitcnt lgkmcnt(2)
	v_mfma_f32_16x16x32_bf16 v[206:209], v[214:217], v[156:159], v[206:209]
	ds_read_b128 v[214:217], v168 offset:13248
	v_max3_f32 v196, v196, v204, v205
	v_mov_b32_e32 v234, v196
	s_nop 1
	v_permlane16_swap_b32_e32 v196, v234
	v_max_f32_e32 v234, v234, v234
	v_max_f32_e32 v196, v196, v196
	s_waitcnt lgkmcnt(2)
	v_mfma_f32_16x16x32_bf16 v[210:213], v[230:233], v[156:159], v[210:213]
	v_max_f32_e32 v196, v196, v234
	v_mov_b32_e32 v168, v196
	s_nop 1
	v_permlane32_swap_b32_e32 v196, v168
	s_waitcnt lgkmcnt(1)
	v_mfma_f32_16x16x32_bf16 v[206:209], v[226:229], v[184:187], v[206:209]
	v_max3_f32 v196, v167, v196, v168
	v_sub_f32_e32 v167, v167, v196
	v_exp_f32_e32 v167, v167
	s_waitcnt lgkmcnt(0)
	v_mfma_f32_16x16x32_bf16 v[210:213], v[214:217], v[184:187], v[210:213]
	s_nop 2
	v_fmamk_f32 v168, v206, 0x3e0293ee, v197
	v_add_f32_e32 v206, 0, v168
	v_fmamk_f32 v168, v207, 0x3e0293ee, v197
	v_add_f32_e32 v207, s86, v168
	v_fmamk_f32 v208, v208, 0x3e0293ee, v197
	v_fmamk_f32 v209, v209, 0x3e0293ee, v197
	v_add_f32_e32 v208, s88, v208
	v_add_f32_e32 v209, s89, v209
	v_fmamk_f32 v210, v210, 0x3e0293ee, v197
	v_fmamk_f32 v211, v211, 0x3e0293ee, v197
	v_max3_f32 v168, v206, s33, v207
	v_add_f32_e32 v210, s87, v210
	v_add_f32_e32 v211, s90, v211
	v_fmamk_f32 v212, v212, 0x3e0293ee, v197
	v_fmac_f32_e32 v197, 0x3e0293ee, v213
	v_max3_f32 v168, v168, v208, v209
	v_add_f32_e32 v212, v161, v212
	v_add_f32_e32 v213, v193, v197
	v_max3_f32 v168, v168, v210, v211
	v_max3_f32 v168, v168, v212, v213
	v_mov_b32_e32 v197, v168
	s_nop 1
	v_permlane16_swap_b32_e32 v168, v197
	v_max_f32_e32 v197, v197, v197
	v_max_f32_e32 v168, v168, v168
	v_max_f32_e32 v168, v168, v197
	v_mov_b32_e32 v197, v168
	s_nop 1
	v_permlane32_swap_b32_e32 v168, v197
	v_max3_f32 v197, v166, v168, v197
	v_sub_f32_e32 v166, v166, v197
	v_exp_f32_e32 v166, v166
	s_branch .Latt_s1done
.Latt_diag:
	v_add_u32_e32 v168, s43, v178
	ds_read_b128 v[196:199], v168
	ds_read_b128 v[208:211], v168 offset:64
	ds_read_b128 v[212:215], v168 offset:4352
	ds_read_b128 v[216:219], v168 offset:4416
	v_cvt_f32_i32_e32 v224, v194
	s_waitcnt lgkmcnt(3)
	v_mfma_f32_16x16x32_bf16 v[196:199], v[196:199], v[240:243], 0
	s_cmp_gt_u32 s39, s37
	v_cmp_gt_i32_e32 vcc, 0, v194
	s_cselect_b64 s[44:45], -1, 0
	s_waitcnt lgkmcnt(1)
	v_mfma_f32_16x16x32_bf16 v[200:203], v[212:215], v[240:243], 0
	ds_read_b128 v[212:215], v168 offset:128
	s_and_b64 vcc, s[44:45], vcc
	v_cmp_gt_i32_e64 s[4:5], 1, v194
	v_mfma_f32_16x16x32_bf16 v[196:199], v[208:211], v[244:247], v[196:199]
	ds_read_b128 v[220:223], v168 offset:192
	s_and_b64 s[4:5], s[44:45], s[4:5]
	v_cmp_gt_i32_e64 s[6:7], 2, v194
	s_waitcnt lgkmcnt(2)
	v_mfma_f32_16x16x32_bf16 v[200:203], v[216:219], v[244:247], v[200:203]
	ds_read_b128 v[216:219], v168 offset:4480
	v_cmp_gt_i32_e64 s[8:9], 3, v194
	v_cmp_gt_i32_e64 s[0:1], 16, v194
	s_waitcnt lgkmcnt(2)
	v_mfma_f32_16x16x32_bf16 v[196:199], v[212:215], v[248:251], v[196:199]
	ds_read_b128 v[212:215], v168 offset:4544
	s_and_b64 s[6:7], s[44:45], s[6:7]
	s_and_b64 s[8:9], s[44:45], s[8:9]
	s_waitcnt lgkmcnt(1)
	v_mfma_f32_16x16x32_bf16 v[200:203], v[216:219], v[248:251], v[200:203]
	v_cmp_gt_i32_e64 s[10:11], 17, v194
	s_and_b64 s[0:1], s[44:45], s[0:1]
	s_and_b64 s[10:11], s[44:45], s[10:11]
	v_mfma_f32_16x16x32_bf16 v[220:223], v[220:223], v[252:255], v[196:199]
	v_cmp_gt_i32_e64 s[12:13], 18, v194
	v_cmp_gt_i32_e64 s[14:15], 19, v194
	s_and_b64 s[12:13], s[44:45], s[12:13]
	s_waitcnt lgkmcnt(0)
	v_mfma_f32_16x16x32_bf16 v[202:205], v[212:215], v[252:255], v[200:203]
	ds_read_b128 v[206:209], v168 offset:8704
	ds_read_b128 v[214:217], v168 offset:13056
	v_mul_f32_e64 v197, -s86, v224
	v_fmamk_f32 v196, v220, 0x3e0293ee, v197
	v_add_f32_e32 v196, 0, v196
	v_cndmask_b32_e32 v198, v196, v192, vcc
	v_fmamk_f32 v196, v221, 0x3e0293ee, v197
	v_fmamk_f32 v200, v222, 0x3e0293ee, v197
	v_fmamk_f32 v201, v223, 0x3e0293ee, v197
	ds_read_b128 v[222:225], v168 offset:8768
	s_waitcnt lgkmcnt(2)
	v_mfma_f32_16x16x32_bf16 v[206:209], v[206:209], v[148:151], 0
	ds_read_b128 v[226:229], v168 offset:13120
	v_add_f32_e32 v196, s86, v196
	v_cndmask_b32_e64 v199, v196, v192, s[4:5]
	s_waitcnt lgkmcnt(2)
	v_mfma_f32_16x16x32_bf16 v[210:213], v[214:217], v[148:151], 0
	ds_read_b128 v[214:217], v168 offset:8832
	v_add_f32_e32 v200, s88, v200
	v_add_f32_e32 v201, s89, v201
	s_waitcnt lgkmcnt(2)
	v_mfma_f32_16x16x32_bf16 v[206:209], v[222:225], v[152:155], v[206:209]
	ds_read_b128 v[230:233], v168 offset:13184
	v_fmamk_f32 v202, v202, 0x3e0293ee, v197
	v_fmamk_f32 v203, v203, 0x3e0293ee, v197
	v_max3_f32 v196, v198, s33, v199
	v_cndmask_b32_e64 v200, v200, v192, s[6:7]
	v_cndmask_b32_e64 v201, v201, v192, s[8:9]
	v_add_f32_e32 v202, s87, v202
	v_add_f32_e32 v203, s90, v203
	v_fmamk_f32 v204, v204, 0x3e0293ee, v197
	v_fmamk_f32 v205, v205, 0x3e0293ee, v197
	v_max3_f32 v196, v196, v200, v201
	v_cndmask_b32_e64 v202, v202, v192, s[0:1]
	v_cndmask_b32_e64 v203, v203, v192, s[10:11]
	v_add_f32_e32 v204, v161, v204
	v_add_f32_e32 v205, v193, v205
	s_and_b64 s[14:15], s[44:45], s[14:15]
	s_waitcnt lgkmcnt(2)
	v_mfma_f32_16x16x32_bf16 v[210:213], v[226:229], v[152:155], v[210:213]
	ds_read_b128 v[226:229], v168 offset:8896
	v_max3_f32 v196, v196, v202, v203
	v_cndmask_b32_e64 v204, v204, v192, s[12:13]
	s_waitcnt lgkmcnt(2)
	v_mfma_f32_16x16x32_bf16 v[206:209], v[214:217], v[156:159], v[206:209]
	ds_read_b128 v[214:217], v168 offset:13248
	v_cndmask_b32_e64 v205, v205, v192, s[14:15]
	v_max3_f32 v196, v196, v204, v205
	v_mov_b32_e32 v234, v196
	s_nop 1
	v_permlane16_swap_b32_e32 v196, v234
	v_max_f32_e32 v234, v234, v234
	v_max_f32_e32 v196, v196, v196
	s_waitcnt lgkmcnt(2)
	v_mfma_f32_16x16x32_bf16 v[210:213], v[230:233], v[156:159], v[210:213]
	v_max_f32_e32 v196, v196, v234
	v_mov_b32_e32 v168, v196
	s_nop 1
	v_permlane32_swap_b32_e32 v196, v168
	s_waitcnt lgkmcnt(1)
	v_mfma_f32_16x16x32_bf16 v[206:209], v[226:229], v[184:187], v[206:209]
	v_max3_f32 v196, v167, v196, v168
	v_sub_f32_e32 v167, v167, v196
	v_exp_f32_e32 v167, v167
	s_waitcnt lgkmcnt(0)
	v_mfma_f32_16x16x32_bf16 v[210:213], v[214:217], v[184:187], v[210:213]
	s_nop 2
	v_fmamk_f32 v168, v206, 0x3e0293ee, v197
	v_add_f32_e32 v168, 0, v168
	v_cndmask_b32_e32 v206, v168, v192, vcc
	v_fmamk_f32 v168, v207, 0x3e0293ee, v197
	v_add_f32_e32 v168, s86, v168
	v_fmamk_f32 v208, v208, 0x3e0293ee, v197
	v_fmamk_f32 v209, v209, 0x3e0293ee, v197
	v_cndmask_b32_e64 v207, v168, v192, s[4:5]
	v_add_f32_e32 v208, s88, v208
	v_add_f32_e32 v209, s89, v209
	v_fmamk_f32 v210, v210, 0x3e0293ee, v197
	v_fmamk_f32 v211, v211, 0x3e0293ee, v197
	v_max3_f32 v168, v206, s33, v207
	v_cndmask_b32_e64 v208, v208, v192, s[6:7]
	v_cndmask_b32_e64 v209, v209, v192, s[8:9]
	v_add_f32_e32 v210, s87, v210
	v_add_f32_e32 v211, s90, v211
	v_fmamk_f32 v212, v212, 0x3e0293ee, v197
	v_fmac_f32_e32 v197, 0x3e0293ee, v213
	v_max3_f32 v168, v168, v208, v209
	v_cndmask_b32_e64 v210, v210, v192, s[0:1]
	v_cndmask_b32_e64 v211, v211, v192, s[10:11]
	v_add_f32_e32 v212, v161, v212
	v_add_f32_e32 v197, v193, v197
	v_max3_f32 v168, v168, v210, v211
	v_cndmask_b32_e64 v212, v212, v192, s[12:13]
	v_cndmask_b32_e64 v213, v197, v192, s[14:15]
	v_max3_f32 v168, v168, v212, v213
	v_mov_b32_e32 v197, v168
	s_nop 1
	v_permlane16_swap_b32_e32 v168, v197
	v_max_f32_e32 v197, v197, v197
	v_max_f32_e32 v168, v168, v168
	v_max_f32_e32 v168, v168, v197
	v_mov_b32_e32 v197, v168
	s_nop 1
	v_permlane32_swap_b32_e32 v168, v197
	v_max3_f32 v197, v166, v168, v197
	v_sub_f32_e32 v166, v166, v197
	v_exp_f32_e32 v166, v166

	.amdhsa_kernel _Z8mega_fwd4Args
		.amdhsa_group_segment_fixed_size 20480
		.amdhsa_private_segment_fixed_size 0
		.amdhsa_kernarg_size 392
		.amdhsa_user_sgpr_count 2
		.amdhsa_user_sgpr_dispatch_ptr 0
		.amdhsa_user_sgpr_queue_ptr 0
		.amdhsa_user_sgpr_kernarg_segment_ptr 1
		.amdhsa_user_sgpr_dispatch_id 0
		.amdhsa_user_sgpr_kernarg_preload_length 0
		.amdhsa_user_sgpr_kernarg_preload_offset 0
		.amdhsa_user_sgpr_private_segment_size 0
		.amdhsa_uses_dynamic_stack 0
		.amdhsa_enable_private_segment 0
		.amdhsa_system_sgpr_workgroup_id_x 1
		.amdhsa_system_sgpr_workgroup_id_y 0
		.amdhsa_system_sgpr_workgroup_id_z 0
		.amdhsa_system_sgpr_workgroup_info 0
		.amdhsa_system_vgpr_workitem_id 2
		.amdhsa_next_free_vgpr 256
		.amdhsa_next_free_sgpr 100
		.amdhsa_accum_offset 256
		.amdhsa_reserve_vcc 1
		.amdhsa_float_round_mode_32 0
		.amdhsa_float_round_mode_16_64 0
		.amdhsa_float_denorm_mode_32 3
		.amdhsa_float_denorm_mode_16_64 3
		.amdhsa_dx10_clamp 1
		.amdhsa_ieee_mode 1
		.amdhsa_fp16_overflow 0
		.amdhsa_tg_split 0
		.amdhsa_exception_fp_ieee_invalid_op 0
		.amdhsa_exception_fp_denorm_src 0
		.amdhsa_exception_fp_ieee_div_zero 0
		.amdhsa_exception_fp_ieee_overflow 0
		.amdhsa_exception_fp_ieee_underflow 0
		.amdhsa_exception_fp_ieee_inexact 0
		.amdhsa_exception_int_div_zero 0
	.end_amdhsa_kernel

amdhsa.kernels:
  - .agpr_count:     0
    .args:
      - .offset:         0
        .size:           136
        .value_kind:     by_value
      - .offset:         136
        .size:           4
        .value_kind:     hidden_block_count_x
      - .offset:         140
        .size:           4
        .value_kind:     hidden_block_count_y
      - .offset:         144
        .size:           4
        .value_kind:     hidden_block_count_z
      - .offset:         148
        .size:           2
        .value_kind:     hidden_group_size_x
      - .offset:         150
        .size:           2
        .value_kind:     hidden_group_size_y
      - .offset:         152
        .size:           2
        .value_kind:     hidden_group_size_z
      - .offset:         154
        .size:           2
        .value_kind:     hidden_remainder_x
      - .offset:         156
        .size:           2
        .value_kind:     hidden_remainder_y
      - .offset:         158
        .size:           2
        .value_kind:     hidden_remainder_z
      - .offset:         176
        .size:           8
        .value_kind:     hidden_global_offset_x
      - .offset:         184
        .size:           8
        .value_kind:     hidden_global_offset_y
      - .offset:         192
        .size:           8
        .value_kind:     hidden_global_offset_z
      - .offset:         200
        .size:           2
        .value_kind:     hidden_grid_dims
      - .offset:         224
        .size:           8
        .value_kind:     hidden_multigrid_sync_arg
      - .offset:         256
        .size:           4
        .value_kind:     hidden_dynamic_lds_size
    .group_segment_fixed_size: 20480
    .kernarg_segment_align: 8
    .kernarg_segment_size: 392
    .language:       OpenCL C
    .language_version:
      - 2
      - 0
    .max_flat_workgroup_size: 512
    .name:           _Z8mega_fwd4Args
    .private_segment_fixed_size: 0
    .sgpr_count:     106
    .sgpr_spill_count: 31
    .symbol:         _Z8mega_fwd4Args.kd
    .uniform_work_group_size: 1
    .uses_dynamic_stack: false
    .vgpr_count:     256
    .vgpr_spill_count: 0
    .wavefront_size: 64
